# speedup vs baseline: 1.0126x; 1.0048x over previous
; __device__ __forceinline__ int otid() { int t = threadIdx.x; asm volatile("" : "+v"(t)); return t; }
; __device__ void phase_peer(const Params& p, int l, float* xout, char* smem) {
;   const int lane = otid() & 63, w = otid() >> 6;
;   int* sel_e = (int*)smem + w * 256;
;   float* sel_g = (float*)(sel_e + 128);
;   const unsigned char* Ub = p.Ub + (long)l * 16384 * UROW;
;   const unsigned char* Vb = p.Vb + (long)l * 16384 * VROW;
;   const float* g2 = p.ln2_g + l * D_;
;   const float* b2 = p.ln2_b + l * D_;
;   for (int t = blockIdx.x * 8 + w; t < S_; t += gridDim.x * 8) {
;     float ts[16]; int ti[16];
;     u32x4 xraw[4];
;     {
;       float v[32];
;       const _Float16* sc = (const _Float16*)p.SC + (long)t * D_ + lane * 32;
; #pragma unroll
;       for (int i = 0; i < 4; ++i) {
;         typedef _Float16 h8 __attribute__((ext_vector_type(8)));
;         const h8 a = *(const h8*)(sc + 8 * i);
; #pragma unroll
;         for (int j = 0; j < 8; ++j) v[8 * i + j] = (float)a[j];
;       }
; #pragma unroll
;       for (int i = 0; i < 4; ++i) xraw[i] = *(const u32x4*)(p.X1b + (long)t * D_ + lane * 32 + i * 8);
;       const int kb = (lane & 3) * 32;
.LBB0_1255:
	s_or_b64 exec, exec, s[0:1]
	s_waitcnt lgkmcnt(0)
	v_mov_b32_e32 v0, v207
	v_mov_b32_e32 v1, v207
	s_barrier
	v_readlane_b32 s0, v252, 40
	v_ashrrev_i32_e32 v1, 6, v1
	s_nop 0
	v_add_u32_e32 v72, s0, v1
	v_cmp_gt_i32_e32 vcc, s83, v72
	s_and_saveexec_b64 s[0:1], vcc
	s_movk_i32 s78, 0x3fff
	s_cbranch_execz .LBB0_1270
	v_readfirstlane_b32 s100, v207
	s_nop 0
	s_lshr_b32 s100, s100, 8
	s_cmp_eq_u32 s100, 0
	s_cbranch_scc1 .Lmy_nostag
	s_movk_i32 s100, 2
.Lmy_stag:
	s_sleep 127
	s_add_i32 s100, s100, -1
	s_cmp_lg_u32 s100, 0
	s_cbranch_scc1 .Lmy_stag
.Lmy_nostag:
	v_readlane_b32 s2, v250, 10
	s_lshl_b32 s2, s2, 14
	s_mul_i32 s3, s2, 0xa80
	v_readlane_b32 s16, v252, 0
	v_readlane_b32 s17, v252, 1
	s_add_u32 s42, s16, s3
	v_readlane_b32 s18, v252, 2
	s_addc_u32 s43, s17, 0
	s_mulk_i32 s2, 0x640
	v_readlane_b32 s19, v252, 3
	v_readlane_b32 s20, v252, 4
	v_readlane_b32 s21, v252, 5
	v_readlane_b32 s22, v252, 6
	v_readlane_b32 s23, v252, 7
	s_add_u32 s90, s42, 0x440
	s_addc_u32 s91, s43, 0
	v_readlane_b32 s16, v252, 24
	s_lshl_b64 s[2:3], s[6:7], 2
	v_readlane_b32 s28, v252, 36
	v_readlane_b32 s29, v252, 37
	s_add_u32 s40, s28, s2
	v_readlane_b32 s20, v252, 28
	v_readlane_b32 s21, v252, 29
	v_readlane_b32 s26, v252, 34
	s_addc_u32 s41, s29, s3
	v_readlane_b32 s17, v252, 25
	v_readlane_b32 s18, v252, 26
	v_readlane_b32 s19, v252, 27
	v_readlane_b32 s27, v252, 35
	v_readlane_b32 s20, v251, 54
	s_add_u32 s66, s26, s2
	v_and_b32_e32 v74, 63, v0
	v_lshlrev_b32_e32 v3, 5, v0
	v_lshlrev_b32_e32 v2, 10, v1
	v_readlane_b32 s21, v251, 55
	s_addc_u32 s67, s27, s3
	v_and_b32_e32 v198, 0x60, v3
	v_and_b32_e32 v3, 4, v0
	s_movk_i32 s4, 0x1500
	v_lshlrev_b32_e32 v176, 7, v74
	v_readlane_b32 s16, v250, 6
	v_add_u32_e32 v79, 16, v2
	v_cmp_eq_u32_e64 s[2:3], 0, v3
	v_mul_lo_u32 v1, v1, s4
	v_lshlrev_b32_e32 v3, 2, v74
	v_bfe_u32 v78, v0, 2, 1
	v_and_b32_e32 v0, 7, v0
	s_cmp_lg_u64 s[20:21], 0
	v_lshl_add_u64 v[80:81], s[66:67], 0, v[176:177]
	v_lshl_add_u64 v[82:83], s[40:41], 0, v[176:177]
	v_lshlrev_b32_e32 v176, 6, v74
	v_readlane_b32 s17, v250, 7
	v_lshlrev_b32_e32 v76, 5, v74
	v_add3_u32 v199, v79, v1, v3
	v_cmp_eq_u32_e64 s[38:39], 0, v0
	v_mov_b32_e32 v75, v177
	s_mov_b64 s[86:87], 0
	s_cselect_b64 s[88:89], -1, 0
	v_lshl_add_u32 v200, v74, 3, v79
	v_lshl_add_u64 v[84:85], s[36:37], 0, v[176:177]
	v_lshl_add_u64 v[86:87], s[16:17], 0, v[176:177]
	v_mov_b32_e32 v77, v78
	v_lshl_add_u64 v[88:89], s[54:55], 0, v[176:177]
	v_add3_u32 v201, 16, 8, v2
	v_readlane_b32 s22, v252, 30
	v_readlane_b32 s23, v252, 31
	v_readlane_b32 s24, v252, 32
	v_readlane_b32 s25, v252, 33
	v_readlane_b32 s30, v252, 38
	v_readlane_b32 s31, v252, 39
	v_readlane_b32 s18, v250, 8
	v_readlane_b32 s19, v250, 9
	s_branch .LBB0_1258
